# rwkv_post loop rewritten: 4 tokens per iteration, loads issued together, DPP row_bcast wave sums instead of ds_bpermute butterflies (f32, different summation order)
# speedup vs baseline: 1.0178x; 1.0178x over previous
; DEVI float bf2f(bf16_t b) { return __uint_as_float(((unsigned)b) << 16); }
; DEVI void rwkv_post(const Params& p, int l, int bid, int nb) {
;     int tid_ = threadIdx.x; asm volatile("" : "+v"(tid_)); size_t wz_ = 0; asm volatile("" : "+s"(wz_)); unsigned char* ws_ = p.ws + wz_;
;     const int wid = tid_ >> 6, lane = tid_ & 63, c = wid * 64 + lane;
;     const bf16_t* R = (const bf16_t*)(ws_ + OFF_RWR); const bf16_t* Kb = (const bf16_t*)(ws_ + OFF_RWK); const bf16_t* Vb = (const bf16_t*)(ws_ + OFF_RWV);
;     const bf16_t* Gb = (const bf16_t*)(ws_ + OFF_RWG); const float* Y = (const float*)(ws_ + OFF_RWY);
;     bf16_t* O = (bf16_t*)(ws_ + OFF_ORWKV);
;     const float rk = ((const float*)p.in[18])[l * 512 + c], lw = ((const float*)p.in[19])[l * 512 + c], lb = ((const float*)p.in[20])[l * 512 + c];
;     for (int tok = bid; tok < S; tok += nb) {
;         const size_t o = (size_t)tok * 512 + c;
;         const float y = Y[o], r = bf2f(R[o]), k = bf2f(Kb[o]), v = bf2f(Vb[o]), g = bf2f(Gb[o]);
;         const float mean = wave_sum(y) * (1.0f / 64.0f);
;         const float dv = y - mean;
;         const float var = wave_sum(dv * dv) * (1.0f / 64.0f);
;         const float yn = dv * rsqrtf(var + 64e-5f) * lw + lb;
;         const float bonus = wave_sum(r * k * rk) * v;
.LBB0_796:
	s_or_b64 exec, exec, s[0:1]
	v_readlane_b32 s0, v254, 43
	v_readlane_b32 s1, v254, 44
	v_mov_b32_e32 v4, v199
	s_mov_b64 s[6:7], 0
	s_andn2_b64 vcc, exec, s[0:1]
	s_barrier
	s_cbranch_vccnz .LBB0_799
	v_readlane_b32 s0, v253, 44
	v_readlane_b32 s6, v255, 60
	v_readlane_b32 s7, v255, 61
	v_lshl_add_u32 v0, s0, 9, v4
	v_ashrrev_i32_e32 v1, 31, v0
	v_lshlrev_b64 v[0:1], 2, v[0:1]
	v_lshl_add_u64 v[2:3], s[56:57], 0, v[0:1]
	global_load_dword v6, v[2:3], off
	v_lshl_add_u64 v[2:3], s[60:61], 0, v[0:1]
	v_lshl_add_u64 v[0:1], s[58:59], 0, v[0:1]
	global_load_dword v7, v[2:3], off
	global_load_dword v1, v[0:1], off
	v_readlane_b32 s8, v255, 62
	v_readlane_b32 s9, v255, 63
	v_lshlrev_b32_e32 v0, 4, v4
	ds_write_b128 v0, v[22:25]
	ds_write_b128 v0, v[26:29] offset:8192
	ds_write_b128 v0, v[30:33] offset:16384
	ds_write_b128 v0, v[34:37] offset:24576
	v_lshlrev_b32_e32 v2, 2, v4
	v_lshlrev_b32_e32 v9, 1, v4
	v_add_u32_e32 v3, 0x2bf00000, v9
	v_add_u32_e32 v5, 0x2df00000, v9
	v_add_u32_e32 v8, 0x30f00000, v9
	v_add_u32_e32 v4, 0x2cf00000, v9
	v_add_u32_e32 v9, 0x29700000, v9
	s_mov_b32 s0, s82
	s_waitcnt lgkmcnt(0)
	v_mov_b32_e32 v0, 0x3a27c5ac
.Lpost_loop:
	s_mov_b64 s[10:11], s[8:9]
	s_mov_b32 s1, s0
	s_cmpk_lt_i32 s1, 0x4000
	s_cbranch_scc0 .Lpost_ld_done
	global_load_dword v10, v2, s[6:7]
	global_load_ushort v14, v3, s[8:9]
	global_load_ushort v18, v4, s[8:9]
	global_load_ushort v22, v5, s[8:9]
	global_load_ushort v26, v8, s[8:9]
	s_add_u32 s6, s6, s48
	s_addc_u32 s7, s7, s49
	s_add_u32 s8, s8, s50
	s_addc_u32 s9, s9, s51
	s_add_i32 s1, s1, s90
	s_cmpk_lt_i32 s1, 0x4000
	s_cbranch_scc0 .Lpost_ld_done
	global_load_dword v11, v2, s[6:7]
	global_load_ushort v15, v3, s[8:9]
	global_load_ushort v19, v4, s[8:9]
	global_load_ushort v23, v5, s[8:9]
	global_load_ushort v27, v8, s[8:9]
	s_add_u32 s6, s6, s48
	s_addc_u32 s7, s7, s49
	s_add_u32 s8, s8, s50
	s_addc_u32 s9, s9, s51
	s_add_i32 s1, s1, s90
	s_cmpk_lt_i32 s1, 0x4000
	s_cbranch_scc0 .Lpost_ld_done
	global_load_dword v12, v2, s[6:7]
	global_load_ushort v16, v3, s[8:9]
	global_load_ushort v20, v4, s[8:9]
	global_load_ushort v24, v5, s[8:9]
	global_load_ushort v28, v8, s[8:9]
	s_add_u32 s6, s6, s48
	s_addc_u32 s7, s7, s49
	s_add_u32 s8, s8, s50
	s_addc_u32 s9, s9, s51
	s_add_i32 s1, s1, s90
	s_cmpk_lt_i32 s1, 0x4000
	s_cbranch_scc0 .Lpost_ld_done
	global_load_dword v13, v2, s[6:7]
	global_load_ushort v17, v3, s[8:9]
	global_load_ushort v21, v4, s[8:9]
	global_load_ushort v25, v5, s[8:9]
	global_load_ushort v29, v8, s[8:9]
	s_add_u32 s6, s6, s48
	s_addc_u32 s7, s7, s49
	s_add_u32 s8, s8, s50
	s_addc_u32 s9, s9, s51
	s_add_i32 s1, s1, s90
.Lpost_ld_done:
	s_waitcnt vmcnt(0)
	v_lshlrev_b32_e32 v14, 16, v14
	v_lshlrev_b32_e32 v18, 16, v18
	v_lshlrev_b32_e32 v22, 16, v22
	v_lshlrev_b32_e32 v26, 16, v26
	v_lshlrev_b32_e32 v15, 16, v15
	v_lshlrev_b32_e32 v19, 16, v19
	v_lshlrev_b32_e32 v23, 16, v23
	v_lshlrev_b32_e32 v27, 16, v27
	v_lshlrev_b32_e32 v16, 16, v16
	v_lshlrev_b32_e32 v20, 16, v20
	v_lshlrev_b32_e32 v24, 16, v24
	v_lshlrev_b32_e32 v28, 16, v28
	v_lshlrev_b32_e32 v17, 16, v17
	v_lshlrev_b32_e32 v21, 16, v21
	v_lshlrev_b32_e32 v25, 16, v25
	v_lshlrev_b32_e32 v29, 16, v29
	v_mul_f32_e32 v34, v18, v14
	v_mul_f32_e32 v35, v19, v15
	v_mul_f32_e32 v36, v20, v16
	v_mul_f32_e32 v37, v21, v17
	v_mul_f32_e32 v34, v6, v34
	v_mul_f32_e32 v35, v6, v35
	v_mul_f32_e32 v36, v6, v36
	v_mul_f32_e32 v37, v6, v37
	v_mov_b32_e32 v30, v10
	v_mov_b32_e32 v31, v11
	v_mov_b32_e32 v32, v12
	v_mov_b32_e32 v33, v13
	v_add_f32_dpp v30, v30, v30 quad_perm:[1,0,3,2] row_mask:0xf bank_mask:0xf bound_ctrl:1
	v_add_f32_dpp v31, v31, v31 quad_perm:[1,0,3,2] row_mask:0xf bank_mask:0xf bound_ctrl:1
	v_add_f32_dpp v32, v32, v32 quad_perm:[1,0,3,2] row_mask:0xf bank_mask:0xf bound_ctrl:1
	v_add_f32_dpp v33, v33, v33 quad_perm:[1,0,3,2] row_mask:0xf bank_mask:0xf bound_ctrl:1
	v_add_f32_dpp v34, v34, v34 quad_perm:[1,0,3,2] row_mask:0xf bank_mask:0xf bound_ctrl:1
	v_add_f32_dpp v35, v35, v35 quad_perm:[1,0,3,2] row_mask:0xf bank_mask:0xf bound_ctrl:1
	v_add_f32_dpp v36, v36, v36 quad_perm:[1,0,3,2] row_mask:0xf bank_mask:0xf bound_ctrl:1
	v_add_f32_dpp v37, v37, v37 quad_perm:[1,0,3,2] row_mask:0xf bank_mask:0xf bound_ctrl:1
	v_add_f32_dpp v30, v30, v30 quad_perm:[2,3,0,1] row_mask:0xf bank_mask:0xf bound_ctrl:1
	v_add_f32_dpp v31, v31, v31 quad_perm:[2,3,0,1] row_mask:0xf bank_mask:0xf bound_ctrl:1
	v_add_f32_dpp v32, v32, v32 quad_perm:[2,3,0,1] row_mask:0xf bank_mask:0xf bound_ctrl:1
	v_add_f32_dpp v33, v33, v33 quad_perm:[2,3,0,1] row_mask:0xf bank_mask:0xf bound_ctrl:1
	v_add_f32_dpp v34, v34, v34 quad_perm:[2,3,0,1] row_mask:0xf bank_mask:0xf bound_ctrl:1
	v_add_f32_dpp v35, v35, v35 quad_perm:[2,3,0,1] row_mask:0xf bank_mask:0xf bound_ctrl:1
	v_add_f32_dpp v36, v36, v36 quad_perm:[2,3,0,1] row_mask:0xf bank_mask:0xf bound_ctrl:1
	v_add_f32_dpp v37, v37, v37 quad_perm:[2,3,0,1] row_mask:0xf bank_mask:0xf bound_ctrl:1
	v_add_f32_dpp v30, v30, v30 row_half_mirror row_mask:0xf bank_mask:0xf bound_ctrl:1
	v_add_f32_dpp v31, v31, v31 row_half_mirror row_mask:0xf bank_mask:0xf bound_ctrl:1
	v_add_f32_dpp v32, v32, v32 row_half_mirror row_mask:0xf bank_mask:0xf bound_ctrl:1
	v_add_f32_dpp v33, v33, v33 row_half_mirror row_mask:0xf bank_mask:0xf bound_ctrl:1
	v_add_f32_dpp v34, v34, v34 row_half_mirror row_mask:0xf bank_mask:0xf bound_ctrl:1
	v_add_f32_dpp v35, v35, v35 row_half_mirror row_mask:0xf bank_mask:0xf bound_ctrl:1
	v_add_f32_dpp v36, v36, v36 row_half_mirror row_mask:0xf bank_mask:0xf bound_ctrl:1
	v_add_f32_dpp v37, v37, v37 row_half_mirror row_mask:0xf bank_mask:0xf bound_ctrl:1
; DEVI float bf2f(bf16_t b) { return __uint_as_float(((unsigned)b) << 16); }
; DEVI bf16_t f2bf(float f) { return (bf16_t)cvt_pk_bf16(f, 0.f); }
; DEVI void rwkv_post(const Params& p, int l, int bid, int nb) {
;     ...
;         const size_t o = (size_t)tok * 512 + c;
;         const float y = Y[o], r = bf2f(R[o]), k = bf2f(Kb[o]), v = bf2f(Vb[o]), g = bf2f(Gb[o]);
;         const float mean = wave_sum(y) * (1.0f / 64.0f);
;         const float dv = y - mean;
;         const float var = wave_sum(dv * dv) * (1.0f / 64.0f);
;         const float yn = dv * rsqrtf(var + 64e-5f) * lw + lb;
;         const float bonus = wave_sum(r * k * rk) * v;
;         O[o] = f2bf((yn + bonus) * g);
	v_add_f32_dpp v30, v30, v30 row_mirror row_mask:0xf bank_mask:0xf bound_ctrl:1
	v_add_f32_dpp v31, v31, v31 row_mirror row_mask:0xf bank_mask:0xf bound_ctrl:1
	v_add_f32_dpp v32, v32, v32 row_mirror row_mask:0xf bank_mask:0xf bound_ctrl:1
	v_add_f32_dpp v33, v33, v33 row_mirror row_mask:0xf bank_mask:0xf bound_ctrl:1
	v_add_f32_dpp v34, v34, v34 row_mirror row_mask:0xf bank_mask:0xf bound_ctrl:1
	v_add_f32_dpp v35, v35, v35 row_mirror row_mask:0xf bank_mask:0xf bound_ctrl:1
	v_add_f32_dpp v36, v36, v36 row_mirror row_mask:0xf bank_mask:0xf bound_ctrl:1
	v_add_f32_dpp v37, v37, v37 row_mirror row_mask:0xf bank_mask:0xf bound_ctrl:1
	v_add_f32_dpp v30, v30, v30 row_bcast:15 row_mask:0xa bank_mask:0xf
	v_add_f32_dpp v31, v31, v31 row_bcast:15 row_mask:0xa bank_mask:0xf
	v_add_f32_dpp v32, v32, v32 row_bcast:15 row_mask:0xa bank_mask:0xf
	v_add_f32_dpp v33, v33, v33 row_bcast:15 row_mask:0xa bank_mask:0xf
	v_add_f32_dpp v34, v34, v34 row_bcast:15 row_mask:0xa bank_mask:0xf
	v_add_f32_dpp v35, v35, v35 row_bcast:15 row_mask:0xa bank_mask:0xf
	v_add_f32_dpp v36, v36, v36 row_bcast:15 row_mask:0xa bank_mask:0xf
	v_add_f32_dpp v37, v37, v37 row_bcast:15 row_mask:0xa bank_mask:0xf
	v_add_f32_dpp v30, v30, v30 row_bcast:31 row_mask:0xc bank_mask:0xf
	v_add_f32_dpp v31, v31, v31 row_bcast:31 row_mask:0xc bank_mask:0xf
	v_add_f32_dpp v32, v32, v32 row_bcast:31 row_mask:0xc bank_mask:0xf
	v_add_f32_dpp v33, v33, v33 row_bcast:31 row_mask:0xc bank_mask:0xf
	v_add_f32_dpp v34, v34, v34 row_bcast:31 row_mask:0xc bank_mask:0xf
	v_add_f32_dpp v35, v35, v35 row_bcast:31 row_mask:0xc bank_mask:0xf
	v_add_f32_dpp v36, v36, v36 row_bcast:31 row_mask:0xc bank_mask:0xf
	v_add_f32_dpp v37, v37, v37 row_bcast:31 row_mask:0xc bank_mask:0xf
	s_nop 0
	v_readlane_b32 s1, v30, 63
	v_readlane_b32 s2, v31, 63
	v_readlane_b32 s3, v32, 63
	v_readlane_b32 s100, v33, 63
	v_mov_b32_e32 v30, s1
	v_mov_b32_e32 v31, s2
	v_mov_b32_e32 v32, s3
	v_mov_b32_e32 v33, s100
	s_nop 0
	v_readlane_b32 s1, v34, 63
	v_readlane_b32 s2, v35, 63
	v_readlane_b32 s3, v36, 63
	v_readlane_b32 s100, v37, 63
	v_mov_b32_e32 v34, s1
	v_mov_b32_e32 v35, s2
	v_mov_b32_e32 v36, s3
	v_mov_b32_e32 v37, s100
	v_fmac_f32_e32 v10, 0xbc800000, v30
	v_fmac_f32_e32 v11, 0xbc800000, v31
	v_fmac_f32_e32 v12, 0xbc800000, v32
	v_fmac_f32_e32 v13, 0xbc800000, v33
	v_mul_f32_e32 v30, v10, v10
	v_mul_f32_e32 v31, v11, v11
	v_mul_f32_e32 v32, v12, v12
	v_mul_f32_e32 v33, v13, v13
	v_add_f32_dpp v30, v30, v30 quad_perm:[1,0,3,2] row_mask:0xf bank_mask:0xf bound_ctrl:1
	v_add_f32_dpp v31, v31, v31 quad_perm:[1,0,3,2] row_mask:0xf bank_mask:0xf bound_ctrl:1
	v_add_f32_dpp v32, v32, v32 quad_perm:[1,0,3,2] row_mask:0xf bank_mask:0xf bound_ctrl:1
	v_add_f32_dpp v33, v33, v33 quad_perm:[1,0,3,2] row_mask:0xf bank_mask:0xf bound_ctrl:1
	v_add_f32_dpp v30, v30, v30 quad_perm:[2,3,0,1] row_mask:0xf bank_mask:0xf bound_ctrl:1
	v_add_f32_dpp v31, v31, v31 quad_perm:[2,3,0,1] row_mask:0xf bank_mask:0xf bound_ctrl:1
	v_add_f32_dpp v32, v32, v32 quad_perm:[2,3,0,1] row_mask:0xf bank_mask:0xf bound_ctrl:1
	v_add_f32_dpp v33, v33, v33 quad_perm:[2,3,0,1] row_mask:0xf bank_mask:0xf bound_ctrl:1
	v_add_f32_dpp v30, v30, v30 row_half_mirror row_mask:0xf bank_mask:0xf bound_ctrl:1
	v_add_f32_dpp v31, v31, v31 row_half_mirror row_mask:0xf bank_mask:0xf bound_ctrl:1
	v_add_f32_dpp v32, v32, v32 row_half_mirror row_mask:0xf bank_mask:0xf bound_ctrl:1
	v_add_f32_dpp v33, v33, v33 row_half_mirror row_mask:0xf bank_mask:0xf bound_ctrl:1
	v_add_f32_dpp v30, v30, v30 row_mirror row_mask:0xf bank_mask:0xf bound_ctrl:1
	v_add_f32_dpp v31, v31, v31 row_mirror row_mask:0xf bank_mask:0xf bound_ctrl:1
	v_add_f32_dpp v32, v32, v32 row_mirror row_mask:0xf bank_mask:0xf bound_ctrl:1
	v_add_f32_dpp v33, v33, v33 row_mirror row_mask:0xf bank_mask:0xf bound_ctrl:1
	v_add_f32_dpp v30, v30, v30 row_bcast:15 row_mask:0xa bank_mask:0xf
	v_add_f32_dpp v31, v31, v31 row_bcast:15 row_mask:0xa bank_mask:0xf
	v_add_f32_dpp v32, v32, v32 row_bcast:15 row_mask:0xa bank_mask:0xf
	v_add_f32_dpp v33, v33, v33 row_bcast:15 row_mask:0xa bank_mask:0xf
	v_add_f32_dpp v30, v30, v30 row_bcast:31 row_mask:0xc bank_mask:0xf
	v_add_f32_dpp v31, v31, v31 row_bcast:31 row_mask:0xc bank_mask:0xf
	v_add_f32_dpp v32, v32, v32 row_bcast:31 row_mask:0xc bank_mask:0xf
	v_add_f32_dpp v33, v33, v33 row_bcast:31 row_mask:0xc bank_mask:0xf
	s_nop 0
	v_readlane_b32 s1, v30, 63
	v_readlane_b32 s2, v31, 63
	v_readlane_b32 s3, v32, 63
	v_readlane_b32 s100, v33, 63
	v_mov_b32_e32 v30, s1
	v_mov_b32_e32 v31, s2
	v_mov_b32_e32 v32, s3
	v_mov_b32_e32 v33, s100
	v_fmamk_f32 v30, v30, 0x3c800000, v0
	v_fmamk_f32 v31, v31, 0x3c800000, v0
	v_fmamk_f32 v32, v32, 0x3c800000, v0
	v_fmamk_f32 v33, v33, 0x3c800000, v0
	v_cmp_gt_f32_e32 vcc, 0x800000, v30
	v_mul_f32_e32 v14, 0x4b800000, v30
	s_nop 0
	v_cndmask_b32_e32 v30, v30, v14, vcc
	v_rsq_f32_e32 v30, v30
	s_nop 0
	v_mul_f32_e32 v14, 0x45800000, v30
	v_cndmask_b32_e32 v30, v30, v14, vcc
	v_cmp_gt_f32_e32 vcc, 0x800000, v31
	v_mul_f32_e32 v15, 0x4b800000, v31
	s_nop 0
	v_cndmask_b32_e32 v31, v31, v15, vcc
	v_rsq_f32_e32 v31, v31
	s_nop 0
	v_mul_f32_e32 v15, 0x45800000, v31
	v_cndmask_b32_e32 v31, v31, v15, vcc
	v_cmp_gt_f32_e32 vcc, 0x800000, v32
	v_mul_f32_e32 v16, 0x4b800000, v32
	s_nop 0
	v_cndmask_b32_e32 v32, v32, v16, vcc
	v_rsq_f32_e32 v32, v32
	s_nop 0
	v_mul_f32_e32 v16, 0x45800000, v32
	v_cndmask_b32_e32 v32, v32, v16, vcc
	v_cmp_gt_f32_e32 vcc, 0x800000, v33
	v_mul_f32_e32 v17, 0x4b800000, v33
	s_nop 0
	v_cndmask_b32_e32 v33, v33, v17, vcc
	v_rsq_f32_e32 v33, v33
	s_nop 0
	v_mul_f32_e32 v17, 0x45800000, v33
	v_cndmask_b32_e32 v33, v33, v17, vcc
	v_mul_f32_e32 v10, v10, v30
	v_mul_f32_e32 v11, v11, v31
	v_mul_f32_e32 v12, v12, v32
	v_mul_f32_e32 v13, v13, v33
	v_mul_f32_e32 v34, v34, v22
	v_mul_f32_e32 v35, v35, v23
	v_mul_f32_e32 v36, v36, v24
	v_mul_f32_e32 v37, v37, v25
	v_mul_f32_e32 v10, v10, v1
	v_mul_f32_e32 v11, v11, v1
	v_mul_f32_e32 v12, v12, v1
	v_mul_f32_e32 v13, v13, v1
	v_add_f32_e32 v10, v7, v10
	v_add_f32_e32 v11, v7, v11
	v_add_f32_e32 v12, v7, v12
	v_add_f32_e32 v13, v7, v13
	v_add_f32_e32 v10, v34, v10
	v_add_f32_e32 v11, v35, v11
	v_add_f32_e32 v12, v36, v12
	v_add_f32_e32 v13, v37, v13
	v_mul_f32_e32 v10, v10, v26
	v_mul_f32_e32 v11, v11, v27
	v_mul_f32_e32 v12, v12, v28
	v_mul_f32_e32 v13, v13, v29
	v_cvt_pk_bf16_f32 v10, v10, v10
	v_cvt_pk_bf16_f32 v11, v11, v11
	v_cvt_pk_bf16_f32 v12, v12, v12
	v_cvt_pk_bf16_f32 v13, v13, v13
	s_mov_b32 s1, s0
	s_cmpk_lt_i32 s1, 0x4000
	s_cbranch_scc0 .Lpost_st_done
; DEVI float bf2f(bf16_t b) { return __uint_as_float(((unsigned)b) << 16); }
; DEVI bf16_t f2bf(float f) { return (bf16_t)cvt_pk_bf16(f, 0.f); }
; DEVI void rwkv_post(const Params& p, int l, int bid, int nb) {
;     ...
;     for (int tok = bid; tok < S; tok += nb) {
;         const size_t o = (size_t)tok * 512 + c;
;         const float y = Y[o], r = bf2f(R[o]), k = bf2f(Kb[o]), v = bf2f(Vb[o]), g = bf2f(Gb[o]);
;         const float mean = wave_sum(y) * (1.0f / 64.0f);
;         const float dv = y - mean;
;         const float var = wave_sum(dv * dv) * (1.0f / 64.0f);
;         const float yn = dv * rsqrtf(var + 64e-5f) * lw + lb;
;         const float bonus = wave_sum(r * k * rk) * v;
;         O[o] = f2bf((yn + bonus) * g);
	global_store_short v9, v10, s[10:11]
	s_add_u32 s10, s10, s50
	s_addc_u32 s11, s11, s51
	s_add_i32 s1, s1, s90
	s_cmpk_lt_i32 s1, 0x4000
	s_cbranch_scc0 .Lpost_st_done
	global_store_short v9, v11, s[10:11]
	s_add_u32 s10, s10, s50
	s_addc_u32 s11, s11, s51
	s_add_i32 s1, s1, s90
	s_cmpk_lt_i32 s1, 0x4000
	s_cbranch_scc0 .Lpost_st_done
	global_store_short v9, v12, s[10:11]
	s_add_u32 s10, s10, s50
	s_addc_u32 s11, s11, s51
	s_add_i32 s1, s1, s90
	s_cmpk_lt_i32 s1, 0x4000
	s_cbranch_scc0 .Lpost_st_done
	global_store_short v9, v13, s[10:11]
	s_add_u32 s10, s10, s50
	s_addc_u32 s11, s11, s51
	s_add_i32 s1, s1, s90
.Lpost_st_done:
	s_lshl_b32 s1, s90, 2
	s_add_i32 s0, s0, s1
	s_cmpk_lt_i32 s0, 0x4000
	s_cbranch_scc1 .Lpost_loop
	v_lshlrev_b32_e32 v0, 4, v199
	ds_read_b128 v[22:25], v0
	ds_read_b128 v[26:29], v0 offset:8192
	ds_read_b128 v[30:33], v0 offset:16384
	ds_read_b128 v[34:37], v0 offset:24576
	s_waitcnt lgkmcnt(0)

; __global__ void __launch_bounds__(512, 2) fwd_megakernel(Params p) {
	.amdhsa_kernel _Z14fwd_megakernel6Params
		.amdhsa_group_segment_fixed_size 0
		.amdhsa_private_segment_fixed_size 0
		.amdhsa_kernarg_size 536
		.amdhsa_user_sgpr_count 2
		.amdhsa_user_sgpr_dispatch_ptr 0
		.amdhsa_user_sgpr_queue_ptr 0
		.amdhsa_user_sgpr_kernarg_segment_ptr 1
		.amdhsa_user_sgpr_dispatch_id 0
		.amdhsa_user_sgpr_kernarg_preload_length 0
		.amdhsa_user_sgpr_kernarg_preload_offset 0
		.amdhsa_user_sgpr_private_segment_size 0
		.amdhsa_uses_dynamic_stack 0
		.amdhsa_enable_private_segment 0
		.amdhsa_system_sgpr_workgroup_id_x 1
		.amdhsa_system_sgpr_workgroup_id_y 0
		.amdhsa_system_sgpr_workgroup_id_z 0
		.amdhsa_system_sgpr_workgroup_info 0
		.amdhsa_system_vgpr_workitem_id 2
		.amdhsa_next_free_vgpr 256
		.amdhsa_next_free_sgpr 102
		.amdhsa_accum_offset 256
		.amdhsa_reserve_vcc 1
		.amdhsa_float_round_mode_32 0
		.amdhsa_float_round_mode_16_64 0
		.amdhsa_float_denorm_mode_32 3
		.amdhsa_float_denorm_mode_16_64 3
		.amdhsa_dx10_clamp 1
		.amdhsa_ieee_mode 1
		.amdhsa_fp16_overflow 0
		.amdhsa_tg_split 0
		.amdhsa_exception_fp_ieee_invalid_op 0
		.amdhsa_exception_fp_denorm_src 0
		.amdhsa_exception_fp_ieee_div_zero 0
		.amdhsa_exception_fp_ieee_overflow 0
		.amdhsa_exception_fp_ieee_underflow 0
		.amdhsa_exception_fp_ieee_inexact 0
		.amdhsa_exception_int_div_zero 0
	.end_amdhsa_kernel

; __global__ void __launch_bounds__(512, 2) fwd_megakernel(Params p) {
amdhsa.kernels:
  - .agpr_count:     0
    .args:
      - .offset:         0
        .size:           280
        .value_kind:     by_value
      - .offset:         280
        .size:           4
        .value_kind:     hidden_block_count_x
      - .offset:         284
        .size:           4
        .value_kind:     hidden_block_count_y
      - .offset:         288
        .size:           4
        .value_kind:     hidden_block_count_z
      - .offset:         292
        .size:           2
        .value_kind:     hidden_group_size_x
      - .offset:         294
        .size:           2
        .value_kind:     hidden_group_size_y
      - .offset:         296
        .size:           2
        .value_kind:     hidden_group_size_z
      - .offset:         298
        .size:           2
        .value_kind:     hidden_remainder_x
      - .offset:         300
        .size:           2
        .value_kind:     hidden_remainder_y
      - .offset:         302
        .size:           2
        .value_kind:     hidden_remainder_z
      - .offset:         320
        .size:           8
        .value_kind:     hidden_global_offset_x
      - .offset:         328
        .size:           8
        .value_kind:     hidden_global_offset_y
      - .offset:         336
        .size:           8
        .value_kind:     hidden_global_offset_z
      - .offset:         344
        .size:           2
        .value_kind:     hidden_grid_dims
      - .offset:         368
        .size:           8
        .value_kind:     hidden_multigrid_sync_arg
      - .offset:         400
        .size:           4
        .value_kind:     hidden_dynamic_lds_size
    .group_segment_fixed_size: 0
    .kernarg_segment_align: 8
    .kernarg_segment_size: 536
    .language:       OpenCL C
    .language_version:
      - 2
      - 0
    .max_flat_workgroup_size: 512
    .name:           _Z14fwd_megakernel6Params
    .private_segment_fixed_size: 0
    .sgpr_count:     108
    .sgpr_spill_count: 255
    .symbol:         _Z14fwd_megakernel6Params.kd
    .uniform_work_group_size: 1
    .uses_dynamic_stack: false
    .vgpr_count:     256
    .vgpr_spill_count: 0
    .wavefront_size: 64
